# as v165 plus the HD-wait and adaLN-wait acquires reduced to L1-only invalidates (no stale L2 copies of those lines can exist: H is not read between the mixer barrier and the HD wait; the adaLN vectors
# speedup vs baseline: 1.0060x; 1.0060x over previous
.LBB0_164:
	buffer_inv sc0
	s_waitcnt vmcnt(0)
